# mixer phase: every workgroup runs its pool unit before its RNN unit (pool reads the freshly written projection while it is still cache resident)
# speedup vs baseline: 1.0086x; 1.0010x over previous
.LBB0_81:
	s_andn2_b64 vcc, exec, s[0:1]
	s_cbranch_vccnz .LBB0_147
	v_readlane_b32 s0, v253, 37
	v_readlane_b32 s1, v253, 38
	s_andn2_b64 vcc, exec, s[0:1]
	s_cbranch_vccnz .LBB0_147
	s_mov_b32 s100, s62
	s_mov_b32 s101, s64
	s_ashr_i32 s65, s64, 31
	s_lshl_b32 s15, s64, 5
	s_lshl_b32 s2, s64, 10
	s_lshl_b64 s[10:11], s[64:65], 12
	s_lshl_b64 s[0:1], s[64:65], 14
	s_mov_b32 s6, s62
	v_readlane_b32 s52, v253, 15
	v_readlane_b32 s58, v253, 21
	v_readlane_b32 s59, v253, 22
	v_readlane_b32 s66, v253, 29
	s_mov_b64 s[58:59], s[10:11]
	v_readlane_b32 s67, v253, 30
	s_add_u32 s34, s66, s58
	v_readlane_b32 s56, v253, 19
	v_readlane_b32 s57, v253, 20
	v_readlane_b32 s64, v253, 27
	s_addc_u32 s35, s67, s59
	v_readlane_b32 s53, v253, 16
	v_readlane_b32 s54, v253, 17
	v_readlane_b32 s55, v253, 18
	v_readlane_b32 s65, v253, 28
	s_add_u32 s18, s64, s0
	v_readlane_b32 s56, v255, 27
	s_mov_b32 s55, s6
	s_addc_u32 s19, s65, s1
	v_readlane_b32 s22, v253, 0
	v_readlane_b32 s52, v255, 22
	v_readlane_b32 s53, v255, 23
	v_readlane_b32 s54, v255, 24
	v_readlane_b32 s57, v255, 28
	v_readlane_b32 s60, v253, 23
	v_readlane_b32 s61, v253, 24
	v_readlane_b32 s62, v253, 25
	v_readlane_b32 s63, v253, 26
	v_readlane_b32 s23, v253, 0
	s_cmp_eq_u32 s23, s23
	s_cbranch_scc1 .LBB0_117
	s_branch .LBB0_85

.Lmix_pool_done:
	v_readlane_b32 s20, v253, 0
	s_cmp_eq_u32 s20, s20
	s_cbranch_scc0 .LBB0_146
	s_mov_b32 s62, s100
	s_mov_b32 s64, s101
	s_ashr_i32 s65, s64, 31
	s_lshl_b32 s15, s64, 5
	s_lshl_b32 s2, s64, 10
	s_lshl_b64 s[10:11], s[64:65], 12
	s_lshl_b64 s[0:1], s[64:65], 14
	s_mov_b32 s6, s62
	v_readlane_b32 s52, v253, 15
	v_readlane_b32 s58, v253, 21
	v_readlane_b32 s59, v253, 22
	v_readlane_b32 s66, v253, 29
	s_mov_b64 s[58:59], s[10:11]
	v_readlane_b32 s67, v253, 30
	s_add_u32 s34, s66, s58
	v_readlane_b32 s56, v253, 19
	v_readlane_b32 s57, v253, 20
	v_readlane_b32 s64, v253, 27
	s_addc_u32 s35, s67, s59
	v_readlane_b32 s53, v253, 16
	v_readlane_b32 s54, v253, 17
	v_readlane_b32 s55, v253, 18
	v_readlane_b32 s65, v253, 28
	s_add_u32 s18, s64, s0
	v_readlane_b32 s56, v255, 27
	s_mov_b32 s55, s6
	s_addc_u32 s19, s65, s1
	v_readlane_b32 s22, v253, 0
	v_readlane_b32 s52, v255, 22
	v_readlane_b32 s53, v255, 23
	v_readlane_b32 s54, v255, 24
	v_readlane_b32 s57, v255, 28
	v_readlane_b32 s60, v253, 23
	v_readlane_b32 s61, v253, 24
	v_readlane_b32 s62, v253, 25
	v_readlane_b32 s63, v253, 26
	s_branch .LBB0_85
.Lmix_rnn_done:
	v_readlane_b32 s23, v253, 0
	s_cmp_eq_u32 s23, s23
	s_cbranch_scc0 .LBB0_117
	v_readlane_b32 s22, v255, 32
	v_readlane_b32 s23, v255, 33
	s_movk_i32 s61, 0xfff
	s_branch .LBB0_146
